# rotated tile loops: two alternating LDS transposition buffers, the barrier behind the store dropped (kept only on loop exit)
# speedup vs baseline: 1.0036x; 1.0004x over previous
; __device__ __forceinline__ unsigned cvt_pk_bf16(float lo, float hi) { unsigned r; asm volatile("v_cvt_pk_bf16_f32 %0, %1, %2" : "=v"(r) : "v"(lo), "v"(hi)); return r; }
; __device__ __forceinline__ int early_tile(int k) { if (k < 1472) return k; k -= 1472; if (k < 704) return 2880 + k; k -= 704; if (k < 256) return 4288 + k; k -= 256; if (k < 64) return 4800 + k; k -= 64; return 4928 + k; }
; __device__ __forceinline__ void transpose_tile(const float* src, int ldsrc, int k0, int n0, bf16_t* dst, int ldd, const float* gain, int rowmode, float* T) {
;     ...
;     { const int n = tid >> 3, k8 = (tid & 7) * 8; const float* tp = T + n * 65 + k8; u32x4 w;
;         w.x = cvt_pk_bf16(tp[0], tp[1]); w.y = cvt_pk_bf16(tp[2], tp[3]); w.z = cvt_pk_bf16(tp[4], tp[5]); w.w = cvt_pk_bf16(tp[6], tp[7]);
;         const int nn = n0 + n; int row;
;         if (rowmode == 1) row = (nn >> 7) * 256 + (nn & 127);
;         else if (rowmode == 2) row = (nn >> 7) * 256 + 128 + (nn & 127);
;         else if (rowmode == 3) row = nn < 1024 ? nn : (nn < 2048 ? nn + 1024 : nn - 1024);
;         else row = nn;
;         *(u32x4*)(dst + (size_t)row * ldd + k0 + k8) = w; }
;     __syncthreads();
; __device__ __forceinline__ void prep_weights(const Params& P, float* T) {
;     ...
;         else { for (int k = blockIdx.x - 16; k < N_EARLY - 128; k += 240) weight_tile(P, early_tile(k), T); }
.Lrot0_save:
	v_mov_b32_e32 v200, s20
	v_mov_b32_e32 v201, s36
	v_mov_b32_e32 v202, s37
	v_mov_b32_e32 v204, s34
	v_mov_b32_e32 v205, s35
	s_lshl_b32 s100, s41, 1
	v_mov_b32_e32 v206, s100
	v_mov_b32_e32 v207, 0
	s_mov_b32 s97, s74
	s_bitset1_b32 s32, 0
	v_xor_b32_e32 v11, 0x8000, v11
	s_addk_i32 s3, 0xf0
	s_addk_i32 s63, 0xf0
	s_cmpk_gt_i32 s72, 0xb4f
	s_cbranch_scc1 .Lrot0_last
	s_branch .LBB0_1190

; __device__ __forceinline__ int early_tile(int k) { if (k < 1472) return k; k -= 1472; if (k < 704) return 2880 + k; k -= 704; if (k < 256) return 4288 + k; k -= 256; if (k < 64) return 4800 + k; k -= 64; return 4928 + k; }
; __device__ __forceinline__ void transpose_tile(const float* src, int ldsrc, int k0, int n0, bf16_t* dst, int ldd, const float* gain, int rowmode, float* T) {
;     ...
;         *(u32x4*)(dst + (size_t)row * ldd + k0 + k8) = w; }
;     __syncthreads();
; __device__ __forceinline__ void prep_weights(const Params& P, float* T) {
;     ...
;         else { for (int k = blockIdx.x - 16; k < N_EARLY - 128; k += 240) weight_tile(P, early_tile(k), T); }
.LBB0_1189:
	v_mad_u64_u32 v[152:153], s[98:99], v201, v151, 0
	v_mov_b32_e32 v150, v153
	v_mad_u64_u32 v[150:151], s[98:99], v202, v151, v[150:151]
	v_mov_b32_e32 v153, v150
	v_lshl_add_u64 v[150:151], v[152:153], 1, v[204:205]
	v_lshl_add_u64 v[150:151], v[150:151], 0, v[206:207]
	v_lshl_add_u64 v[150:151], v[150:151], 0, v[6:7]
	global_store_dwordx4 v[150:151], v[136:139], off
	v_xor_b32_e32 v10, 0x8000, v10
	s_bitcmp1_b32 s32, 1
	s_cbranch_scc0 .Lrot0_mid
	v_and_b32_e32 v11, 0x7fff, v11
	v_and_b32_e32 v10, 0x7fff, v10
	s_barrier
	s_branch .LBB0_1230

; __device__ __forceinline__ unsigned cvt_pk_bf16(float lo, float hi) { unsigned r; asm volatile("v_cvt_pk_bf16_f32 %0, %1, %2" : "=v"(r) : "v"(lo), "v"(hi)); return r; }
; __device__ __forceinline__ int defer_tile(int k) { if (k < 1408) return 1472 + k; k -= 1408; if (k < 704) return 3584 + k; k -= 704; if (k < 256) return 4544 + k; k -= 256; if (k < 64) return 4864 + k; k -= 64; return 5696 + k; }
; #define PHASE(k, ...) if (EN(k) && lo <= (k) && (k) < hi) { constexpr bool dup_ = false; (void)dup_; __VA_ARGS__ if ((k) + 1 < hi) GRID_SYNC(); } if (DUP(k) && lo <= (k) && (k) < hi) { constexpr bool dup_ = true; (void)dup_; __VA_ARGS__ GRID_SYNC(); }
; __device__ __forceinline__ void transpose_tile(const float* src, int ldsrc, int k0, int n0, bf16_t* dst, int ldd, const float* gain, int rowmode, float* T) {
;     ...
;     { const int n = tid >> 3, k8 = (tid & 7) * 8; const float* tp = T + n * 65 + k8; u32x4 w;
;         w.x = cvt_pk_bf16(tp[0], tp[1]); w.y = cvt_pk_bf16(tp[2], tp[3]); w.z = cvt_pk_bf16(tp[4], tp[5]); w.w = cvt_pk_bf16(tp[6], tp[7]);
;         const int nn = n0 + n; int row;
;         if (rowmode == 1) row = (nn >> 7) * 256 + (nn & 127);
;         else if (rowmode == 2) row = (nn >> 7) * 256 + 128 + (nn & 127);
;         else if (rowmode == 3) row = nn < 1024 ? nn : (nn < 2048 ? nn + 1024 : nn - 1024);
;         else row = nn;
;         *(u32x4*)(dst + (size_t)row * ldd + k0 + k8) = w; }
;     __syncthreads();
; __global__ void __launch_bounds__(NT, 2) fwd_kernel(Params P) {
;     ...
;     PHASE(6, gla_g1(P, lds); if (!dup_ && G == 256 && bx >= 64) { __syncthreads(); for (int k = bx - 64; k < N_DEFER; k += 384) weight_tile(P, defer_tile(k), (float*)lds); } )
.Lrot6_save:
	v_mov_b32_e32 v200, s30
	v_mov_b32_e32 v201, s38
	v_mov_b32_e32 v202, s39
	v_mov_b32_e32 v204, s34
	v_mov_b32_e32 v205, s35
	s_lshl_b32 s100, s41, 1
	v_mov_b32_e32 v206, s100
	v_mov_b32_e32 v207, 0
	s_mov_b32 s97, s80
	s_bitset1_b32 s32, 0
	v_xor_b32_e32 v11, 0x8000, v11
	s_add_i32 s30, s79, 0xffffff40
	s_cmpk_lt_i32 s79, 0x900
	s_cselect_b32 s30, s79, s30
	s_add_i32 s3, s30, 0x180
	s_cmpk_lt_i32 s79, 0x9c0
	s_cbranch_scc0 .Lrot6_last
	s_branch .LBB0_1983

; __device__ __forceinline__ unsigned cvt_pk_bf16(float lo, float hi) { unsigned r; asm volatile("v_cvt_pk_bf16_f32 %0, %1, %2" : "=v"(r) : "v"(lo), "v"(hi)); return r; }
; __device__ __forceinline__ int defer_tile(int k) { if (k < 1408) return 1472 + k; k -= 1408; if (k < 704) return 3584 + k; k -= 704; if (k < 256) return 4544 + k; k -= 256; if (k < 64) return 4864 + k; k -= 64; return 5696 + k; }
; #define PHASE(k, ...) if (EN(k) && lo <= (k) && (k) < hi) { constexpr bool dup_ = false; (void)dup_; __VA_ARGS__ if ((k) + 1 < hi) GRID_SYNC(); } if (DUP(k) && lo <= (k) && (k) < hi) { constexpr bool dup_ = true; (void)dup_; __VA_ARGS__ GRID_SYNC(); }
; __device__ __forceinline__ void transpose_tile(const float* src, int ldsrc, int k0, int n0, bf16_t* dst, int ldd, const float* gain, int rowmode, float* T) {
;     ...
;     { const int n = tid >> 3, k8 = (tid & 7) * 8; const float* tp = T + n * 65 + k8; u32x4 w;
;         w.x = cvt_pk_bf16(tp[0], tp[1]); w.y = cvt_pk_bf16(tp[2], tp[3]); w.z = cvt_pk_bf16(tp[4], tp[5]); w.w = cvt_pk_bf16(tp[6], tp[7]);
;         const int nn = n0 + n; int row;
;         if (rowmode == 1) row = (nn >> 7) * 256 + (nn & 127);
;         else if (rowmode == 2) row = (nn >> 7) * 256 + 128 + (nn & 127);
;         else if (rowmode == 3) row = nn < 1024 ? nn : (nn < 2048 ? nn + 1024 : nn - 1024);
;         else row = nn;
;         *(u32x4*)(dst + (size_t)row * ldd + k0 + k8) = w; }
;     __syncthreads();
; __global__ void __launch_bounds__(NT, 2) fwd_kernel(Params P) {
;     ...
;     PHASE(8, gla_g3(P, lds); if (!dup_ && G == 256 && bx >= 64) { __syncthreads(); for (int k = 192 + bx - 64; k < N_DEFER; k += 384) weight_tile(P, defer_tile(k), (float*)lds); } )
.Lrot8_save:
	v_mov_b32_e32 v200, s28
	v_mov_b32_e32 v201, s36
	v_mov_b32_e32 v202, s37
	v_mov_b32_e32 v204, s30
	v_mov_b32_e32 v205, s31
	s_lshl_b32 s100, s39, 1
	v_mov_b32_e32 v206, s100
	v_mov_b32_e32 v207, 0
	s_mov_b32 s97, s79
	s_bitset1_b32 s32, 0
	v_xor_b32_e32 v10, 0x8000, v10
	s_add_i32 s28, s46, 0x180
	s_cmpk_lt_i32 s46, 0x840
	s_mov_b32 s46, s28
	s_cbranch_scc0 .Lrot8_last
	s_branch .LBB0_2186

; __device__ __forceinline__ int defer_tile(int k) { if (k < 1408) return 1472 + k; k -= 1408; if (k < 704) return 3584 + k; k -= 704; if (k < 256) return 4544 + k; k -= 256; if (k < 64) return 4864 + k; k -= 64; return 5696 + k; }
; #define PHASE(k, ...) if (EN(k) && lo <= (k) && (k) < hi) { constexpr bool dup_ = false; (void)dup_; __VA_ARGS__ if ((k) + 1 < hi) GRID_SYNC(); } if (DUP(k) && lo <= (k) && (k) < hi) { constexpr bool dup_ = true; (void)dup_; __VA_ARGS__ GRID_SYNC(); }
; __device__ __forceinline__ void transpose_tile(const float* src, int ldsrc, int k0, int n0, bf16_t* dst, int ldd, const float* gain, int rowmode, float* T) {
;     ...
;         *(u32x4*)(dst + (size_t)row * ldd + k0 + k8) = w; }
;     __syncthreads();
; __global__ void __launch_bounds__(NT, 2) fwd_kernel(Params P) {
;     ...
;     PHASE(8, gla_g3(P, lds); if (!dup_ && G == 256 && bx >= 64) { __syncthreads(); for (int k = 192 + bx - 64; k < N_DEFER; k += 384) weight_tile(P, defer_tile(k), (float*)lds); } )
.LBB0_2185:
	v_mad_u64_u32 v[152:153], s[98:99], v201, v150, 0
	v_mov_b32_e32 v154, v153
	v_mad_u64_u32 v[150:151], s[98:99], v202, v150, v[154:155]
	v_mov_b32_e32 v153, v150
	v_lshl_add_u64 v[150:151], v[152:153], 1, v[204:205]
	v_lshl_add_u64 v[150:151], v[150:151], 0, v[206:207]
	v_lshl_add_u64 v[150:151], v[150:151], 0, v[6:7]
	global_store_dwordx4 v[150:151], v[136:139], off
	v_xor_b32_e32 v9, 0x8000, v9
	s_bitcmp1_b32 s32, 1
	s_cbranch_scc0 .Lrot8_mid
	v_and_b32_e32 v10, 0x7fff, v10
	v_and_b32_e32 v9, 0x7fff, v9
	s_barrier
	s_branch .LBB0_2222
